# k41 + P0 x->bf16 loop: kernarg pointer loads hoisted out of the loop and the loop software-pipelined (next rows' loads in flight during processing)
# baseline (speedup 1.0000x reference)
; __device__ __forceinline__ unsigned cvt_pk_bf16(float lo, float hi) { unsigned r; asm volatile("v_cvt_pk_bf16_f32 %0, %1, %2" : "=v"(r) : "v"(lo), "v"(hi)); return r; }
; __device__ __forceinline__ unsigned cvt_pk_bf16(float lo, float hi) { const f32x2 v = {lo, hi}; const bf16x2_t b = __builtin_convertvector(v, bf16x2_t); return __builtin_bit_cast(unsigned, b); }
; __device__ __forceinline__ void p0_prologue(Frame& F) {
;     ...
;     for (int m0 = gw; m0 < MT; m0 += 2 * NGW) {
;         f32x4 v[2][4], pv[2]; int mm[2];
; #pragma unroll
;         for (int q = 0; q < 2; ++q) {
;             const int m = (m0 + q * NGW < MT) ? m0 + q * NGW : m0; mm[q] = m;
;             const float* xrow = (m < MP) ? A.in[0] + (size_t)m * D : A.in[1] + (size_t)(m - MP) * D;
;             const float* prow = (m < MP) ? A.in[2] + (size_t)m * DPLE : A.in[3] + (size_t)(m - MP) * DPLE;
; #pragma unroll
;             for (int j = 0; j < 4; ++j) v[q][j] = *((const f32x4*)xrow + F.lane + 64 * j);
;             pv[q] = *((const f32x4*)prow + F.lane);
;         }
; #pragma unroll
;         for (int q = 0; q < 2; ++q) {
;             const int m = mm[q]; float s = 0.f;
; #pragma unroll
;             for (int j = 0; j < 4; ++j) s += (v[q][j][0] * v[q][j][0] + v[q][j][1] * v[q][j][1]) + (v[q][j][2] * v[q][j][2] + v[q][j][3] * v[q][j][3]);
;             s = wave_sum(s);
;             v2u* o8 = (v2u*)(XB + (size_t)m * D) + F.lane;
; #pragma unroll
;             for (int j = 0; j < 4; ++j) { v2u w; w.x = cvt_pk_bf16(v[q][j][0], v[q][j][1]); w.y = cvt_pk_bf16(v[q][j][2], v[q][j][3]); o8[64 * j] = w; }
;             if (F.lane < 16) SS[(size_t)m * 16 + F.lane] = (F.lane == 0) ? s : 0.f;
;             v2u w; w.x = cvt_pk_bf16(pv[q][0], pv[q][1]); w.y = cvt_pk_bf16(pv[q][2], pv[q][3]);
;             *((v2u*)(PE + (size_t)m * DPLE) + F.lane) = w;
;         }
.LBB0_183:
	s_cmpk_gt_i32 s10, 0x43ff
	s_cbranch_scc1 .LBB0_190
	s_load_dwordx8 s[80:87], s[0:1], 0x0
	s_waitcnt vmcnt(8)
	v_mbcnt_lo_u32_b32 v0, -1, 0
	v_mbcnt_hi_u32_b32 v0, -1, v0
	v_and_b32_e32 v1, 64, v0
	v_add_u32_e32 v1, 64, v1
	v_xor_b32_e32 v2, 1, v0
	v_cmp_lt_i32_e32 vcc, v2, v1
	v_and_b32_e32 v4, 63, v192
	s_mov_b64 s[4:5], 0xcb90000
	v_cndmask_b32_e32 v2, v0, v2, vcc
	s_waitcnt vmcnt(6)
	v_lshlrev_b32_e32 v30, 2, v2
	v_xor_b32_e32 v2, 2, v0
	v_cmp_lt_i32_e32 vcc, v2, v1
	v_cmp_eq_u32_e64 s[6:7], 0, v4
	s_waitcnt vmcnt(4)
	v_lshlrev_b32_e32 v36, 4, v4
	v_cndmask_b32_e32 v2, v0, v2, vcc
	v_lshlrev_b32_e32 v31, 2, v2
	v_xor_b32_e32 v2, 4, v0
	v_cmp_lt_i32_e32 vcc, v2, v1
	s_nop 1
	v_cndmask_b32_e32 v2, v0, v2, vcc
	v_lshlrev_b32_e32 v32, 2, v2
	v_xor_b32_e32 v2, 8, v0
	v_cmp_lt_i32_e32 vcc, v2, v1
	s_nop 1
	v_cndmask_b32_e32 v2, v0, v2, vcc
	v_lshlrev_b32_e32 v33, 2, v2
	v_xor_b32_e32 v2, 16, v0
	v_cmp_lt_i32_e32 vcc, v2, v1
	s_nop 1
	v_cndmask_b32_e32 v2, v0, v2, vcc
	v_lshlrev_b32_e32 v34, 2, v2
	v_xor_b32_e32 v2, 32, v0
	v_cmp_lt_i32_e32 vcc, v2, v1
	v_mov_b32_e32 v1, 0
	v_mov_b32_e32 v3, v1
	v_cndmask_b32_e32 v0, v0, v2, vcc
	v_lshlrev_b32_e32 v35, 2, v0
	v_lshlrev_b32_e32 v0, 3, v4
	v_lshl_add_u64 v[24:25], s[34:35], 0, v[0:1]
	v_lshlrev_b32_e32 v2, 2, v4
	v_lshl_add_u64 v[0:1], s[26:27], 0, v[0:1]
	v_cmp_gt_u32_e32 vcc, 16, v4
	v_lshl_add_u64 v[26:27], s[44:45], 0, v[2:3]
	v_lshl_add_u64 v[28:29], v[0:1], 0, s[4:5]
	s_waitcnt lgkmcnt(0)
	s_add_i32 s92, s10, s3
	s_cmpk_lt_i32 s92, 0x4400
	s_cselect_b32 s92, s92, s10
	s_add_i32 s94, s10, 0xffffc000
	s_ashr_i32 s91, s10, 31
	s_cmpk_lt_i32 s10, 0x4000
	s_cselect_b32 s16, s10, s94
	s_cselect_b32 s17, s91, 0
	s_cselect_b32 s18, s80, s82
	s_cselect_b32 s19, s81, s83
	s_cselect_b32 s20, s84, s86
	s_cselect_b32 s21, s85, s87
	s_lshl_b64 s[88:89], s[16:17], 12
	s_add_u32 s18, s18, s88
	s_addc_u32 s19, s19, s89
	s_lshl_b64 s[88:89], s[16:17], 10
	s_add_u32 s20, s20, s88
	s_addc_u32 s21, s21, s89
	s_add_i32 s94, s92, 0xffffc000
	s_ashr_i32 s91, s92, 31
	s_cmpk_lt_i32 s92, 0x4000
	s_cselect_b32 s16, s92, s94
	s_cselect_b32 s17, s91, 0
	s_cselect_b32 s22, s80, s82
	s_cselect_b32 s23, s81, s83
	s_cselect_b32 s96, s84, s86
	s_cselect_b32 s97, s85, s87
	s_lshl_b64 s[88:89], s[16:17], 12
	s_add_u32 s22, s22, s88
	s_addc_u32 s23, s23, s89
	s_lshl_b64 s[88:89], s[16:17], 10
	s_add_u32 s96, s96, s88
	s_addc_u32 s97, s97, s89
	global_load_dwordx4 v[38:41], v36, s[18:19] nt
	global_load_dwordx4 v[42:45], v36, s[18:19] offset:1024 nt
	global_load_dwordx4 v[46:49], v36, s[18:19] offset:2048 nt
	global_load_dwordx4 v[50:53], v36, s[18:19] offset:3072 nt
	global_load_dwordx4 v[20:23], v36, s[20:21] nt
	global_load_dwordx4 v[16:19], v36, s[22:23] nt
	global_load_dwordx4 v[12:15], v36, s[22:23] offset:1024 nt
	global_load_dwordx4 v[4:7], v36, s[22:23] offset:2048 nt
	global_load_dwordx4 v[8:11], v36, s[22:23] offset:3072 nt
	global_load_dwordx4 v[0:3], v36, s[96:97] nt
.Lxa_top:
	s_lshl_b32 s90, s3, 1
	s_add_i32 s90, s10, s90
	s_cmpk_lt_i32 s90, 0x4400
	s_cselect_b32 s90, s90, s10
	s_add_i32 s92, s90, s3
	s_cmpk_lt_i32 s92, 0x4400
	s_cselect_b32 s92, s92, s90
	s_add_i32 s94, s90, 0xffffc000
	s_ashr_i32 s91, s90, 31
	s_cmpk_lt_i32 s90, 0x4000
	s_cselect_b32 s16, s90, s94
	s_cselect_b32 s17, s91, 0
	s_cselect_b32 s18, s80, s82
	s_cselect_b32 s19, s81, s83
	s_cselect_b32 s20, s84, s86
	s_cselect_b32 s21, s85, s87
	s_lshl_b64 s[88:89], s[16:17], 12
	s_add_u32 s18, s18, s88
	s_addc_u32 s19, s19, s89
	s_lshl_b64 s[88:89], s[16:17], 10
	s_add_u32 s20, s20, s88
	s_addc_u32 s21, s21, s89
	s_add_i32 s94, s92, 0xffffc000
	s_ashr_i32 s91, s92, 31
	s_cmpk_lt_i32 s92, 0x4000
	s_cselect_b32 s16, s92, s94
	s_cselect_b32 s17, s91, 0
	s_cselect_b32 s22, s80, s82
	s_cselect_b32 s23, s81, s83
	s_cselect_b32 s96, s84, s86
	s_cselect_b32 s97, s85, s87
	s_lshl_b64 s[88:89], s[16:17], 12
	s_add_u32 s22, s22, s88
	s_addc_u32 s23, s23, s89
	s_lshl_b64 s[88:89], s[16:17], 10
	s_add_u32 s96, s96, s88
	s_addc_u32 s97, s97, s89
	global_load_dwordx4 v[88:91], v36, s[18:19] nt
	global_load_dwordx4 v[92:95], v36, s[18:19] offset:1024 nt
	global_load_dwordx4 v[96:99], v36, s[18:19] offset:2048 nt
	global_load_dwordx4 v[100:103], v36, s[18:19] offset:3072 nt
	global_load_dwordx4 v[84:87], v36, s[20:21] nt
	global_load_dwordx4 v[80:83], v36, s[22:23] nt
	global_load_dwordx4 v[76:79], v36, s[22:23] offset:1024 nt
	global_load_dwordx4 v[68:71], v36, s[22:23] offset:2048 nt
	global_load_dwordx4 v[72:75], v36, s[22:23] offset:3072 nt
	global_load_dwordx4 v[64:67], v36, s[96:97] nt
	s_ashr_i32 s11, s10, 31
	s_add_i32 s4, s10, s3
	s_cmpk_lt_i32 s4, 0x4400
	s_cselect_b32 s12, s4, s10
	s_ashr_i32 s13, s12, 31
	s_lshl_b64 s[14:15], s[10:11], 11
	s_waitcnt vmcnt(19)
	v_mul_f32_e32 v37, v39, v39
	v_mul_f32_e32 v54, v41, v41
	s_waitcnt vmcnt(18)
	v_mul_f32_e32 v55, v43, v43
	v_mul_f32_e32 v56, v45, v45
	s_waitcnt vmcnt(17)
	v_mul_f32_e32 v57, v47, v47
	v_mul_f32_e32 v58, v49, v49
	v_fmac_f32_e32 v37, v38, v38
	v_fmac_f32_e32 v54, v40, v40
	v_fmac_f32_e32 v55, v42, v42
	v_fmac_f32_e32 v56, v44, v44
	s_waitcnt vmcnt(16)
	v_mul_f32_e32 v59, v51, v51
	v_mul_f32_e32 v60, v53, v53
	v_fmac_f32_e32 v57, v46, v46
	v_fmac_f32_e32 v58, v48, v48
	v_add_f32_e32 v37, v37, v54
	v_add_f32_e32 v54, v55, v56
	v_fmac_f32_e32 v59, v50, v50
	v_fmac_f32_e32 v60, v52, v52
	v_add_f32_e32 v55, v57, v58
	v_add_f32_e32 v37, v37, v54
	v_add_f32_e32 v56, v59, v60
	v_add_f32_e32 v37, v37, v55
	v_add_f32_e32 v37, v37, v56
	ds_bpermute_b32 v54, v30, v37
	v_cvt_pk_bf16_f32 v38, v38, v39
	v_cvt_pk_bf16_f32 v39, v40, v41
	v_cvt_pk_bf16_f32 v40, v42, v43
	v_cvt_pk_bf16_f32 v41, v44, v45
	s_waitcnt lgkmcnt(0)
	v_add_f32_e32 v37, v37, v54
	ds_bpermute_b32 v54, v31, v37
	v_cvt_pk_bf16_f32 v42, v46, v47
	s_waitcnt lgkmcnt(0)
	v_add_f32_e32 v37, v37, v54
	ds_bpermute_b32 v54, v32, v37
	s_waitcnt lgkmcnt(0)
	v_add_f32_e32 v37, v37, v54
	ds_bpermute_b32 v56, v33, v37
	v_lshl_add_u64 v[54:55], v[24:25], 0, s[14:15]
	global_store_dwordx2 v[54:55], v[38:39], off sc1
	global_store_dwordx2 v[54:55], v[40:41], off offset:512 sc1
	v_cvt_pk_bf16_f32 v40, v50, v51
	v_cvt_pk_bf16_f32 v41, v52, v53
	s_waitcnt lgkmcnt(0)
	v_add_f32_e32 v37, v37, v56
	ds_bpermute_b32 v43, v34, v37
	global_store_dwordx2 v[54:55], v[40:41], off offset:1536 sc1
	s_waitcnt lgkmcnt(0)
	v_add_f32_e32 v37, v37, v43
	ds_bpermute_b32 v38, v35, v37
	v_cvt_pk_bf16_f32 v43, v48, v49
	global_store_dwordx2 v[54:55], v[42:43], off offset:1024 sc1
	s_and_saveexec_b64 s[14:15], vcc
	s_cbranch_execz .Lxa_8
	s_waitcnt lgkmcnt(0)
	v_add_f32_e32 v37, v37, v38
	s_lshl_b64 s[16:17], s[10:11], 6
	v_lshl_add_u64 v[38:39], v[26:27], 0, s[16:17]
	v_cndmask_b32_e64 v37, 0, v37, s[6:7]
	global_store_dword v[38:39], v37, off
; __device__ __forceinline__ unsigned cvt_pk_bf16(float lo, float hi) { unsigned r; asm volatile("v_cvt_pk_bf16_f32 %0, %1, %2" : "=v"(r) : "v"(lo), "v"(hi)); return r; }
; __device__ __forceinline__ unsigned cvt_pk_bf16(float lo, float hi) { const f32x2 v = {lo, hi}; const bf16x2_t b = __builtin_convertvector(v, bf16x2_t); return __builtin_bit_cast(unsigned, b); }
; __device__ __forceinline__ void p0_prologue(Frame& F) {
;     ...
; #pragma unroll
;         for (int q = 0; q < 2; ++q) {
;             const int m = mm[q]; float s = 0.f;
; #pragma unroll
;             for (int j = 0; j < 4; ++j) s += (v[q][j][0] * v[q][j][0] + v[q][j][1] * v[q][j][1]) + (v[q][j][2] * v[q][j][2] + v[q][j][3] * v[q][j][3]);
;             s = wave_sum(s);
;             v2u* o8 = (v2u*)(XB + (size_t)m * D) + F.lane;
; #pragma unroll
;             for (int j = 0; j < 4; ++j) { v2u w; w.x = cvt_pk_bf16(v[q][j][0], v[q][j][1]); w.y = cvt_pk_bf16(v[q][j][2], v[q][j][3]); o8[64 * j] = w; }
;             if (F.lane < 16) SS[(size_t)m * 16 + F.lane] = (F.lane == 0) ? s : 0.f;
;             v2u w; w.x = cvt_pk_bf16(pv[q][0], pv[q][1]); w.y = cvt_pk_bf16(pv[q][2], pv[q][3]);
;             *((v2u*)(PE + (size_t)m * DPLE) + F.lane) = w;
;         }
.Lxa_8:
	s_or_b64 exec, exec, s[14:15]
	s_waitcnt vmcnt(18)
	v_mul_f32_e32 v37, v17, v17
	s_waitcnt lgkmcnt(0)
	v_mul_f32_e32 v38, v19, v19
	v_fmac_f32_e32 v37, v16, v16
	v_fmac_f32_e32 v38, v18, v18
	v_add_f32_e32 v37, v37, v38
	s_waitcnt vmcnt(17)
	v_mul_f32_e32 v38, v13, v13
	v_mul_f32_e32 v39, v15, v15
	v_fmac_f32_e32 v38, v12, v12
	v_fmac_f32_e32 v39, v14, v14
	v_add_f32_e32 v38, v38, v39
	v_add_f32_e32 v37, v37, v38
	s_waitcnt vmcnt(16)
	v_mul_f32_e32 v38, v5, v5
	v_mul_f32_e32 v39, v7, v7
	v_fmac_f32_e32 v38, v4, v4
	v_fmac_f32_e32 v39, v6, v6
	v_add_f32_e32 v38, v38, v39
	v_add_f32_e32 v37, v37, v38
	s_waitcnt vmcnt(15)
	v_mul_f32_e32 v38, v9, v9
	v_mul_f32_e32 v39, v11, v11
	v_fmac_f32_e32 v38, v8, v8
	v_fmac_f32_e32 v39, v10, v10
	v_add_f32_e32 v38, v38, v39
	v_add_f32_e32 v37, v37, v38
	ds_bpermute_b32 v38, v30, v37
	s_lshl_b64 s[10:11], s[10:11], 9
	v_cvt_pk_bf16_f32 v20, v20, v21
	v_cvt_pk_bf16_f32 v21, v22, v23
	v_lshl_add_u64 v[22:23], v[28:29], 0, s[10:11]
	s_waitcnt lgkmcnt(0)
	v_add_f32_e32 v37, v37, v38
	ds_bpermute_b32 v38, v31, v37
	global_store_dwordx2 v[22:23], v[20:21], off sc1
	s_lshl_b64 s[10:11], s[12:13], 11
	v_lshl_add_u64 v[22:23], v[24:25], 0, s[10:11]
	v_cvt_pk_bf16_f32 v4, v4, v5
	s_waitcnt lgkmcnt(0)
	v_add_f32_e32 v37, v37, v38
	ds_bpermute_b32 v38, v32, v37
	v_cvt_pk_bf16_f32 v5, v6, v7
	v_cvt_pk_bf16_f32 v16, v16, v17
	v_cvt_pk_bf16_f32 v17, v18, v19
	v_cvt_pk_bf16_f32 v12, v12, v13
	s_waitcnt lgkmcnt(0)
	v_add_f32_e32 v37, v37, v38
	ds_bpermute_b32 v38, v33, v37
	v_cvt_pk_bf16_f32 v13, v14, v15
	global_store_dwordx2 v[22:23], v[4:5], off offset:1024 sc1
	v_cvt_pk_bf16_f32 v4, v8, v9
	v_cvt_pk_bf16_f32 v5, v10, v11
	s_waitcnt lgkmcnt(0)
	v_add_f32_e32 v37, v37, v38
	ds_bpermute_b32 v38, v34, v37
	global_store_dwordx2 v[22:23], v[16:17], off sc1
	global_store_dwordx2 v[22:23], v[12:13], off offset:512 sc1
	global_store_dwordx2 v[22:23], v[4:5], off offset:1536 sc1
	s_waitcnt lgkmcnt(0)
	v_add_f32_e32 v20, v37, v38
	ds_bpermute_b32 v21, v35, v20
	s_and_saveexec_b64 s[10:11], vcc
	s_cbranch_execz .Lxa_5
	s_waitcnt lgkmcnt(0)
	v_add_f32_e32 v6, v20, v21
	s_lshl_b64 s[14:15], s[12:13], 6
	v_lshl_add_u64 v[4:5], v[26:27], 0, s[14:15]
	v_cndmask_b32_e64 v6, 0, v6, s[6:7]
	global_store_dword v[4:5], v6, off
	s_branch .Lxa_5
.Lxa_5:
	s_or_b64 exec, exec, s[10:11]
	s_lshl_b64 s[10:11], s[12:13], 9
	s_waitcnt vmcnt(19)
	v_cvt_pk_bf16_f32 v0, v0, v1
	v_cvt_pk_bf16_f32 v1, v2, v3
	v_lshl_add_u64 v[2:3], v[28:29], 0, s[10:11]
	s_add_i32 s10, s4, s3
	s_cmpk_gt_i32 s10, 0x43ff
	global_store_dwordx2 v[2:3], v[0:1], off sc1
	s_cbranch_scc1 .Lx_exit
.Lxb_top:
	s_lshl_b32 s90, s3, 1
	s_add_i32 s90, s10, s90
	s_cmpk_lt_i32 s90, 0x4400
	s_cselect_b32 s90, s90, s10
	s_add_i32 s92, s90, s3
	s_cmpk_lt_i32 s92, 0x4400
	s_cselect_b32 s92, s92, s90
	s_add_i32 s94, s90, 0xffffc000
	s_ashr_i32 s91, s90, 31
	s_cmpk_lt_i32 s90, 0x4000
	s_cselect_b32 s16, s90, s94
	s_cselect_b32 s17, s91, 0
	s_cselect_b32 s18, s80, s82
	s_cselect_b32 s19, s81, s83
	s_cselect_b32 s20, s84, s86
	s_cselect_b32 s21, s85, s87
	s_lshl_b64 s[88:89], s[16:17], 12
	s_add_u32 s18, s18, s88
	s_addc_u32 s19, s19, s89
	s_lshl_b64 s[88:89], s[16:17], 10
	s_add_u32 s20, s20, s88
	s_addc_u32 s21, s21, s89
	s_add_i32 s94, s92, 0xffffc000
	s_ashr_i32 s91, s92, 31
	s_cmpk_lt_i32 s92, 0x4000
	s_cselect_b32 s16, s92, s94
	s_cselect_b32 s17, s91, 0
	s_cselect_b32 s22, s80, s82
	s_cselect_b32 s23, s81, s83
	s_cselect_b32 s96, s84, s86
	s_cselect_b32 s97, s85, s87
	s_lshl_b64 s[88:89], s[16:17], 12
	s_add_u32 s22, s22, s88
	s_addc_u32 s23, s23, s89
	s_lshl_b64 s[88:89], s[16:17], 10
	s_add_u32 s96, s96, s88
	s_addc_u32 s97, s97, s89
	global_load_dwordx4 v[38:41], v36, s[18:19] nt
	global_load_dwordx4 v[42:45], v36, s[18:19] offset:1024 nt
	global_load_dwordx4 v[46:49], v36, s[18:19] offset:2048 nt
	global_load_dwordx4 v[50:53], v36, s[18:19] offset:3072 nt
	global_load_dwordx4 v[20:23], v36, s[20:21] nt
	global_load_dwordx4 v[16:19], v36, s[22:23] nt
	global_load_dwordx4 v[12:15], v36, s[22:23] offset:1024 nt
	global_load_dwordx4 v[4:7], v36, s[22:23] offset:2048 nt
	global_load_dwordx4 v[8:11], v36, s[22:23] offset:3072 nt
	global_load_dwordx4 v[0:3], v36, s[96:97] nt
	s_ashr_i32 s11, s10, 31
	s_add_i32 s4, s10, s3
	s_cmpk_lt_i32 s4, 0x4400
	s_cselect_b32 s12, s4, s10
	s_ashr_i32 s13, s12, 31
	s_lshl_b64 s[14:15], s[10:11], 11
	s_waitcnt vmcnt(19)
	v_mul_f32_e32 v37, v89, v89
	v_mul_f32_e32 v54, v91, v91
	s_waitcnt vmcnt(18)
	v_mul_f32_e32 v55, v93, v93
	v_mul_f32_e32 v56, v95, v95
	s_waitcnt vmcnt(17)
	v_mul_f32_e32 v57, v97, v97
	v_mul_f32_e32 v58, v99, v99
	v_fmac_f32_e32 v37, v88, v88
	v_fmac_f32_e32 v54, v90, v90
	v_fmac_f32_e32 v55, v92, v92
	v_fmac_f32_e32 v56, v94, v94
	s_waitcnt vmcnt(16)
	v_mul_f32_e32 v59, v101, v101
	v_mul_f32_e32 v60, v103, v103
	v_fmac_f32_e32 v57, v96, v96
	v_fmac_f32_e32 v58, v98, v98
	v_add_f32_e32 v37, v37, v54
	v_add_f32_e32 v54, v55, v56
	v_fmac_f32_e32 v59, v100, v100
	v_fmac_f32_e32 v60, v102, v102
	v_add_f32_e32 v55, v57, v58
	v_add_f32_e32 v37, v37, v54
	v_add_f32_e32 v56, v59, v60
	v_add_f32_e32 v37, v37, v55
	v_add_f32_e32 v37, v37, v56
	ds_bpermute_b32 v54, v30, v37
	v_cvt_pk_bf16_f32 v88, v88, v89
	v_cvt_pk_bf16_f32 v89, v90, v91
	v_cvt_pk_bf16_f32 v90, v92, v93
	v_cvt_pk_bf16_f32 v91, v94, v95
	s_waitcnt lgkmcnt(0)
	v_add_f32_e32 v37, v37, v54
	ds_bpermute_b32 v54, v31, v37
	v_cvt_pk_bf16_f32 v92, v96, v97
	s_waitcnt lgkmcnt(0)
	v_add_f32_e32 v37, v37, v54
	ds_bpermute_b32 v54, v32, v37
	s_waitcnt lgkmcnt(0)
	v_add_f32_e32 v37, v37, v54
	ds_bpermute_b32 v56, v33, v37
	v_lshl_add_u64 v[54:55], v[24:25], 0, s[14:15]
	global_store_dwordx2 v[54:55], v[88:89], off sc1
	global_store_dwordx2 v[54:55], v[90:91], off offset:512 sc1
	v_cvt_pk_bf16_f32 v90, v100, v101
	v_cvt_pk_bf16_f32 v91, v102, v103
	s_waitcnt lgkmcnt(0)
	v_add_f32_e32 v37, v37, v56
	ds_bpermute_b32 v93, v34, v37
	global_store_dwordx2 v[54:55], v[90:91], off offset:1536 sc1
	s_waitcnt lgkmcnt(0)
	v_add_f32_e32 v37, v37, v93
	ds_bpermute_b32 v88, v35, v37
	v_cvt_pk_bf16_f32 v93, v98, v99
	global_store_dwordx2 v[54:55], v[92:93], off offset:1024 sc1
	s_and_saveexec_b64 s[14:15], vcc
	s_cbranch_execz .Lxb_8
	s_waitcnt lgkmcnt(0)
	v_add_f32_e32 v37, v37, v88
	s_lshl_b64 s[16:17], s[10:11], 6
	v_lshl_add_u64 v[88:89], v[26:27], 0, s[16:17]
	v_cndmask_b32_e64 v37, 0, v37, s[6:7]
	global_store_dword v[88:89], v37, off
; __device__ __forceinline__ unsigned cvt_pk_bf16(float lo, float hi) { unsigned r; asm volatile("v_cvt_pk_bf16_f32 %0, %1, %2" : "=v"(r) : "v"(lo), "v"(hi)); return r; }
; __device__ __forceinline__ unsigned cvt_pk_bf16(float lo, float hi) { const f32x2 v = {lo, hi}; const bf16x2_t b = __builtin_convertvector(v, bf16x2_t); return __builtin_bit_cast(unsigned, b); }
; __device__ __forceinline__ void p0_prologue(Frame& F) {
;     ...
; #pragma unroll
;         for (int q = 0; q < 2; ++q) {
;             const int m = mm[q]; float s = 0.f;
; #pragma unroll
;             for (int j = 0; j < 4; ++j) s += (v[q][j][0] * v[q][j][0] + v[q][j][1] * v[q][j][1]) + (v[q][j][2] * v[q][j][2] + v[q][j][3] * v[q][j][3]);
;             s = wave_sum(s);
;             v2u* o8 = (v2u*)(XB + (size_t)m * D) + F.lane;
; #pragma unroll
;             for (int j = 0; j < 4; ++j) { v2u w; w.x = cvt_pk_bf16(v[q][j][0], v[q][j][1]); w.y = cvt_pk_bf16(v[q][j][2], v[q][j][3]); o8[64 * j] = w; }
;             if (F.lane < 16) SS[(size_t)m * 16 + F.lane] = (F.lane == 0) ? s : 0.f;
;             v2u w; w.x = cvt_pk_bf16(pv[q][0], pv[q][1]); w.y = cvt_pk_bf16(pv[q][2], pv[q][3]);
;             *((v2u*)(PE + (size_t)m * DPLE) + F.lane) = w;
;         }
;     ...
;     {
;         bf16* WSB = (bf16*)(ws + WS_WSB); const float* wsrc = A.in[14];
;         for (int e = blockIdx.x * (NWAVES * 64) + F.tid; e < 8 * 128 * 128 / 2; e += F.G * NWAVES * 64) {
;             const int t = (e >> 6) & 127, s0 = 2 * (e & 63); const f32x2 v = *(const f32x2*)(wsrc + 2 * e);
;             *(unsigned*)(WSB + 2 * e) = cvt_pk_bf16(s0 <= t ? v[0] : 0.f, s0 + 1 <= t ? v[1] : 0.f);
.Lxb_8:
	s_or_b64 exec, exec, s[14:15]
	s_waitcnt vmcnt(18)
	v_mul_f32_e32 v37, v81, v81
	s_waitcnt lgkmcnt(0)
	v_mul_f32_e32 v88, v83, v83
	v_fmac_f32_e32 v37, v80, v80
	v_fmac_f32_e32 v88, v82, v82
	v_add_f32_e32 v37, v37, v88
	s_waitcnt vmcnt(17)
	v_mul_f32_e32 v88, v77, v77
	v_mul_f32_e32 v89, v79, v79
	v_fmac_f32_e32 v88, v76, v76
	v_fmac_f32_e32 v89, v78, v78
	v_add_f32_e32 v88, v88, v89
	v_add_f32_e32 v37, v37, v88
	s_waitcnt vmcnt(16)
	v_mul_f32_e32 v88, v69, v69
	v_mul_f32_e32 v89, v71, v71
	v_fmac_f32_e32 v88, v68, v68
	v_fmac_f32_e32 v89, v70, v70
	v_add_f32_e32 v88, v88, v89
	v_add_f32_e32 v37, v37, v88
	s_waitcnt vmcnt(15)
	v_mul_f32_e32 v88, v73, v73
	v_mul_f32_e32 v89, v75, v75
	v_fmac_f32_e32 v88, v72, v72
	v_fmac_f32_e32 v89, v74, v74
	v_add_f32_e32 v88, v88, v89
	v_add_f32_e32 v37, v37, v88
	ds_bpermute_b32 v88, v30, v37
	s_lshl_b64 s[10:11], s[10:11], 9
	v_cvt_pk_bf16_f32 v84, v84, v85
	v_cvt_pk_bf16_f32 v85, v86, v87
	v_lshl_add_u64 v[86:87], v[28:29], 0, s[10:11]
	s_waitcnt lgkmcnt(0)
	v_add_f32_e32 v37, v37, v88
	ds_bpermute_b32 v88, v31, v37
	global_store_dwordx2 v[86:87], v[84:85], off sc1
	s_lshl_b64 s[10:11], s[12:13], 11
	v_lshl_add_u64 v[86:87], v[24:25], 0, s[10:11]
	v_cvt_pk_bf16_f32 v68, v68, v69
	s_waitcnt lgkmcnt(0)
	v_add_f32_e32 v37, v37, v88
	ds_bpermute_b32 v88, v32, v37
	v_cvt_pk_bf16_f32 v69, v70, v71
	v_cvt_pk_bf16_f32 v80, v80, v81
	v_cvt_pk_bf16_f32 v81, v82, v83
	v_cvt_pk_bf16_f32 v76, v76, v77
	s_waitcnt lgkmcnt(0)
	v_add_f32_e32 v37, v37, v88
	ds_bpermute_b32 v88, v33, v37
	v_cvt_pk_bf16_f32 v77, v78, v79
	global_store_dwordx2 v[86:87], v[68:69], off offset:1024 sc1
	v_cvt_pk_bf16_f32 v68, v72, v73
	v_cvt_pk_bf16_f32 v69, v74, v75
	s_waitcnt lgkmcnt(0)
	v_add_f32_e32 v37, v37, v88
	ds_bpermute_b32 v88, v34, v37
	global_store_dwordx2 v[86:87], v[80:81], off sc1
	global_store_dwordx2 v[86:87], v[76:77], off offset:512 sc1
	global_store_dwordx2 v[86:87], v[68:69], off offset:1536 sc1
	s_waitcnt lgkmcnt(0)
	v_add_f32_e32 v84, v37, v88
	ds_bpermute_b32 v85, v35, v84
	s_and_saveexec_b64 s[10:11], vcc
	s_cbranch_execz .Lxb_5
	s_waitcnt lgkmcnt(0)
	v_add_f32_e32 v70, v84, v85
	s_lshl_b64 s[14:15], s[12:13], 6
	v_lshl_add_u64 v[68:69], v[26:27], 0, s[14:15]
	v_cndmask_b32_e64 v70, 0, v70, s[6:7]
	global_store_dword v[68:69], v70, off
	s_branch .Lxb_5
.Lxb_5:
	s_or_b64 exec, exec, s[10:11]
	s_lshl_b64 s[10:11], s[12:13], 9
	s_waitcnt vmcnt(19)
	v_cvt_pk_bf16_f32 v64, v64, v65
	v_cvt_pk_bf16_f32 v65, v66, v67
	v_lshl_add_u64 v[66:67], v[28:29], 0, s[10:11]
	s_add_i32 s10, s4, s3
	s_cmpk_gt_i32 s10, 0x43ff
	global_store_dwordx2 v[66:67], v[64:65], off sc1
	s_cbranch_scc1 .Lx_exit
	s_branch .Lxa_top
.Lx_exit:
	s_waitcnt vmcnt(0)
.LBB0_190:
	s_waitcnt vmcnt(8)
	v_lshl_add_u32 v0, s2, 9, v192
	s_mov_b32 s3, 0x10000
	v_cmp_gt_i32_e32 vcc, s3, v0
	s_and_saveexec_b64 s[10:11], vcc
	s_cbranch_execz .LBB0_193
	s_load_dwordx2 s[14:15], s[0:1], 0x70
	s_add_u32 s12, s26, 0xd5a4800
	v_lshlrev_b32_e32 v1, 1, v192
	s_addc_u32 s13, s27, 0
	s_lshl_b32 s3, s30, 9
	v_lshl_add_u32 v2, s2, 10, v1
	s_lshl_b32 s4, s30, 10
	s_mov_b64 s[16:17], 0
	s_mov_b32 s5, 0xffff
	v_mov_b32_e32 v1, v0
